# k7 plus non-blocking next-ticket atomic in the attention unit queue
# speedup vs baseline: 1.0012x; 1.0012x over previous
; __global__ void __launch_bounds__(NWAVES * 64, 2) hybrid_fwd(Args args) {
;     ...
;             unsigned nxt_ = 0u;
;             if (tid == 0) nxt_ = __hip_atomic_fetch_add(qctr, 1u, __ATOMIC_RELAXED, __HIP_MEMORY_SCOPE_AGENT);
.LBB0_690:
	s_mov_b64 s[52:53], exec
	v_mbcnt_lo_u32_b32 v0, s52, 0
	v_mbcnt_hi_u32_b32 v0, s53, v0
	v_cmp_eq_u32_e32 vcc, 0, v0
	s_and_saveexec_b64 s[6:7], vcc
	s_cbranch_execz .LBB0_692
	s_bcnt1_i32_b64 s9, s[52:53]
	v_readlane_b32 s16, v254, 30
	v_mov_b32_e32 v1, s9
	v_readlane_b32 s17, v254, 31
	s_nop 4
	global_atomic_add v208, v2, v1, s[16:17] sc0
.LBB0_692:
	s_or_b64 exec, exec, s[6:7]
	s_or_b64 exec, exec, s[4:5]
	s_bitcmp1_b32 s71, 15
	s_mov_b64 s[4:5], -1
	s_cbranch_scc0 .LBB0_688

; __global__ void __launch_bounds__(NWAVES * 64, 2) hybrid_fwd(Args args) {
;     ...
;             if (tid == 0) qslot[0] = nxt_ < 3072u ? (unsigned)ATT_ORDER[nxt_] : 0xffffffffu;
.LBB0_784:
	v_mbcnt_lo_u32_b32 v0, -1, 0
	v_mbcnt_hi_u32_b32 v0, -1, v0
	s_nop 0
	v_sub_u32_e32 v0, 0, v0
	v_cmp_eq_u32_e32 vcc, s11, v0
	s_and_saveexec_b64 s[4:5], vcc
	s_cbranch_execz .LBB0_684
	s_waitcnt vmcnt(0)
	s_movk_i32 s6, 0xc00
	v_cmp_gt_u32_e32 vcc, s6, v208
	v_mov_b32_e32 v0, -1
	s_and_saveexec_b64 s[6:7], vcc
	s_cbranch_execz .LBB0_683
	v_mov_b32_e32 v209, v2
	s_getpc_b64 s[16:17]
	s_add_u32 s16, s16, _ZL9ATT_ORDER@rel32@lo+4
	s_addc_u32 s17, s17, _ZL9ATT_ORDER@rel32@hi+12
	v_lshl_add_u64 v[0:1], v[208:209], 1, s[16:17]
	global_load_ushort v0, v[0:1], off
	s_branch .LBB0_683
